# v_k3 + grid barrier: waiters poll the global generation word directly (one polling hop less)
# speedup vs baseline: 1.0014x; 1.0014x over previous
; DI unsigned xb_ld(unsigned* p) { return __hip_atomic_load(p, __ATOMIC_RELAXED, __HIP_MEMORY_SCOPE_AGENT); }
; DI unsigned xb_add(unsigned* p, unsigned v) { return __hip_atomic_fetch_add(p, v, __ATOMIC_RELAXED, __HIP_MEMORY_SCOPE_AGENT); }
; #define XB_SPIN(cond, bar) do { unsigned _sp = 0; while (cond) { __builtin_amdgcn_s_sleep(1); \
;     if ((++_sp & 255u) == 0u) { if (xb_ld(&(bar)[XB_TMO])) break; if (_sp > XB_SPIN_CAP) { atomicAdd(&(bar)[XB_TMO], 1u); break; } } } } while (0)
; DI void xcd_barrier(const XcdBarrier& b) {
;     ...
;   if (threadIdx.x == 0) {
;     unsigned* bar = b.bar;
;     __builtin_amdgcn_s_waitcnt(0);
;     unsigned nloc = b.st[0], nx = b.st[1];
;     if (nloc == 0u) { xcd_barrier_complete(bar, b.x, nloc, nx); b.st[0] = nloc; b.st[1] = nx; }
;     const unsigned old = xb_add(&bar[XB_XSUB(b.x)], 1u);
;     const unsigned gen = old / nloc;
;     if (old + 1u == (gen + 1u) * nloc) {
;       __builtin_amdgcn_fence(__ATOMIC_RELEASE, "agent");
;       asm volatile("s_waitcnt vmcnt(0)" ::: "memory");
;       const unsigned og = xb_add(&bar[XB_TOP], 1u);
;       const unsigned tg = og / nx;
;       if (og + 1u == (tg + 1u) * nx) xb_add(&bar[XB_TOPGEN], 1u);
;       else XB_SPIN(xb_ld(&bar[XB_TOPGEN]) == tg, bar);
;       __builtin_amdgcn_fence(__ATOMIC_ACQUIRE, "agent");
;       xb_add(&bar[XB_XGEN(b.x)], 1u);
;       asm volatile("s_waitcnt vmcnt(0)" ::: "memory");
;     } else {
;       XB_SPIN(xb_ld(&bar[XB_XGEN(b.x)]) == gen, bar);
.LBB0_1386:
	s_or_b64 exec, exec, s[12:13]
	v_cvt_f32_u32_e32 v4, v2
	s_waitcnt vmcnt(0)
	v_readfirstlane_b32 s12, v3
	v_sub_u32_e32 v3, 0, v2
	v_rcp_iflag_f32_e32 v4, v4
	v_add_u32_e32 v5, s12, v1
	v_mul_f32_e32 v4, 0x4f7ffffe, v4
	v_cvt_u32_f32_e32 v4, v4
	v_mul_lo_u32 v1, v3, v4
	v_mul_hi_u32 v1, v4, v1
	v_add_u32_e32 v1, v4, v1
	v_mul_hi_u32 v1, v5, v1
	v_mul_lo_u32 v3, v1, v2
	v_sub_u32_e32 v3, v5, v3
	v_add_u32_e32 v4, 1, v1
	v_cmp_ge_u32_e32 vcc, v3, v2
	s_nop 1
	v_cndmask_b32_e32 v1, v1, v4, vcc
	v_sub_u32_e32 v4, v3, v2
	v_cndmask_b32_e32 v3, v3, v4, vcc
	v_add_u32_e32 v4, 1, v1
	v_cmp_ge_u32_e32 vcc, v3, v2
	v_add_u32_e32 v3, 1, v5
	s_nop 0
	v_cndmask_b32_e32 v1, v1, v4, vcc
	v_mul_lo_u32 v4, v2, v1
	v_add_u32_e32 v2, v4, v2
	v_cmp_ne_u32_e32 vcc, v3, v2
	s_and_saveexec_b64 s[12:13], vcc
	s_xor_b64 s[28:29], exec, s[12:13]
	s_cbranch_execz .LBB0_1400
	v_readlane_b32 s12, v254, 11
	v_readlane_b32 s13, v254, 12
	s_waitcnt lgkmcnt(0)
	s_nop 3
	global_load_dword v0, v177, s[12:13] sc1
	s_waitcnt vmcnt(0)
	v_cmp_eq_u32_e32 vcc, v0, v1
	s_and_saveexec_b64 s[36:37], vcc
	s_cbranch_execz .LBB0_1399
	s_mov_b32 s12, 1
	s_mov_b64 s[38:39], 0
	s_branch .LBB0_1390

; DI unsigned xb_ld(unsigned* p) { return __hip_atomic_load(p, __ATOMIC_RELAXED, __HIP_MEMORY_SCOPE_AGENT); }
; #define XB_SPIN(cond, bar) do { unsigned _sp = 0; while (cond) { __builtin_amdgcn_s_sleep(1); \
;     if ((++_sp & 255u) == 0u) { if (xb_ld(&(bar)[XB_TMO])) break; if (_sp > XB_SPIN_CAP) { atomicAdd(&(bar)[XB_TMO], 1u); break; } } } } while (0)
; DI void xcd_barrier(const XcdBarrier& b) {
;     ...
;       XB_SPIN(xb_ld(&bar[XB_XGEN(b.x)]) == gen, bar);
.LBB0_1392:
	v_readlane_b32 s42, v254, 11
	v_readlane_b32 s43, v254, 12
	s_add_i32 s12, s12, 1
	s_mov_b64 s[44:45], -1
	s_nop 2
	global_load_dword v0, v177, s[42:43] sc1
	s_waitcnt vmcnt(0)
	v_cmp_ne_u32_e32 vcc, v0, v1
	s_orn2_b64 s[42:43], vcc, exec
	s_branch .LBB0_1389

; DI unsigned xb_add(unsigned* p, unsigned v) { return __hip_atomic_fetch_add(p, v, __ATOMIC_RELAXED, __HIP_MEMORY_SCOPE_AGENT); }
; DI void xcd_barrier(const XcdBarrier& b) {
;     ...
;       __builtin_amdgcn_fence(__ATOMIC_ACQUIRE, "agent");
;       xb_add(&bar[XB_XGEN(b.x)], 1u);
;       asm volatile("s_waitcnt vmcnt(0)" ::: "memory");
.LBB0_1418:
	s_bcnt1_i32_b64 s12, s[12:13]
	v_mov_b32_e32 v0, s12
	v_readlane_b32 s12, v254, 7
	v_readlane_b32 s13, v254, 8
	s_nop 4
	s_nop 0
	s_getpc_b64 s[98:99]
